# attention pipelined loop + P6 saddr/balanced + a_ready loads moved to epilogue start (P1,P6)
# speedup vs baseline: 1.0228x; 1.0036x over previous
;     __device__ __forceinline__ void a_ready(const Unit& u) const {
;         const float* p = rsv + u.pm * BM + wr_ * 64 + lane_;
;         if (n_ready & 1) { b0 = p[0]; b1 = p[HALF]; } else { a0 = p[0]; a1 = p[HALF]; }
;         ++n_ready;
;     }
; template <class Epi, class Sched, bool ALIGN_EPI = false, bool SP2 = false>
; __device__ __forceinline__ void gemm_phase(PG8_LAS unsigned char* lds, const Gemm g, const Sched& S, const Epi& E) {
;     ...
;             const char* a1 = cA + (size_t)(t + 1) * kstep;
;             const char* a2 = last ? nA : cA + (size_t)(t + 2) * kstep; const char* b2 = last ? nB : cB + (size_t)(t + 2) * kstep;
;             const char* a3 = a2 + kstep; const char* b3 = b2 + kstep;
;             if (last && has_next) S.a_ready(nxt);
.LBB0_183:
	s_cmp_eq_u32 s98, 28
	s_cselect_b64 s[66:67], -1, 0
	s_and_b64 s[68:69], s[2:3], s[66:67]
	s_andn2_b64 vcc, exec, s[68:69]
	s_cbranch_vccnz .LBB0_182
	s_nop 0
	s_branch .LBB0_182

;     __device__ __forceinline__ void a_ready(const Unit& u) const {
;         const float* p = rsv + u.pm * BM + wr_ * 64 + lane_;
;         if (n_ready & 1) { b0 = p[0]; b1 = p[HALF]; } else { a0 = p[0]; a1 = p[HALF]; }
;         ++n_ready;
;     }
;     __device__ __forceinline__ void operator()(const f32x4 (&acc)[2][2][4][2], const Unit& u, int wr, int wc, int fr, int fq) const {
;         const int row0 = u.pm * BM + wr * 64 + fr;
;         const bool par = (n_done & 1) != 0; ++n_done;
;         const float r0 = par ? S->b0 : S->a0, r1 = par ? S->b1 : S->a1;
;         float rs8[8];
; #pragma unroll
;         for (int i = 0; i < 8; ++i) rs8[i] = __builtin_bit_cast(float, __builtin_amdgcn_ds_bpermute(((i & 3) * 16 + fr) << 2, __builtin_bit_cast(int, (i >> 2) ? r1 : r0)));
.LBB0_187:
	s_bitcmp0_b32 s93, 0
	s_cselect_b64 vcc, -1, 0
	s_waitcnt vmcnt(0)
	s_and_b64 s[68:69], s[2:3], exec
	s_cbranch_scc0 .Lp1_noar
	s_bitcmp1_b32 s93, 0
	s_cbranch_scc1 .Lp1_ar_a
	global_load_dword v191, v[156:157], off
	global_load_dword v190, v[156:157], off offset:512
	s_branch .Lp1_noar
.Lp1_ar_a:
	global_load_dword v173, v[156:157], off
	global_load_dword v177, v[156:157], off offset:512
.Lp1_noar:
	v_cndmask_b32_e32 v156, v191, v173, vcc
	v_cndmask_b32_e32 v157, v190, v177, vcc
	ds_bpermute_b32 v176, v185, v156
	ds_bpermute_b32 v172, v187, v156
	ds_bpermute_b32 v168, v188, v156
	ds_bpermute_b32 v164, v189, v156
	ds_bpermute_b32 v162, v185, v157
	ds_bpermute_b32 v160, v187, v157
	ds_bpermute_b32 v158, v188, v157
	ds_bpermute_b32 v156, v189, v157
	v_lshl_add_u32 v178, s26, 8, v184
	v_or_b32_e32 v174, 16, v178
	v_or_b32_e32 v170, 32, v178
	v_or_b32_e32 v166, 48, v178
	s_mov_b64 s[64:65], -1
	s_cmp_gt_i32 s92, 7
	v_ashrrev_i32_e32 v179, 31, v178
	v_ashrrev_i32_e32 v175, 31, v174
	v_ashrrev_i32_e32 v171, 31, v170
	v_ashrrev_i32_e32 v167, 31, v166
	s_cbranch_scc1 .LBB0_190
	s_andn2_b64 vcc, exec, s[64:65]
	s_cbranch_vccz .LBB0_191

;     __device__ __forceinline__ void a_ready(const Unit& u) const {
;         const float* p = rsv + u.pm * BM + wr_ * 64 + lane_;
;         if (n_ready & 1) { b0 = p[0]; b1 = p[HALF]; } else { a0 = p[0]; a1 = p[HALF]; }
;         ++n_ready;
;     }
; template <class Epi, class Sched, bool ALIGN_EPI = false, bool SP2 = false>
; __device__ __forceinline__ void gemm_phase(PG8_LAS unsigned char* lds, const Gemm g, const Sched& S, const Epi& E) {
;     ...
;             const char* a1 = cA + (size_t)(t + 1) * kstep;
;             const char* a2 = last ? nA : cA + (size_t)(t + 2) * kstep; const char* b2 = last ? nB : cB + (size_t)(t + 2) * kstep;
;             const char* a3 = a2 + kstep; const char* b3 = b2 + kstep;
;             if (last && has_next) S.a_ready(nxt);
.LBB0_693:
	s_cmp_eq_u32 s64, 28
	s_cselect_b64 s[26:27], -1, 0
	s_and_b64 s[36:37], s[2:3], s[26:27]
	s_andn2_b64 vcc, exec, s[36:37]
	s_cbranch_vccnz .LBB0_692
	s_nop 0
	s_branch .LBB0_692

; __device__ __forceinline__ float sigmoid_fast(float x) { return __builtin_amdgcn_rcpf(1.0f + __builtin_amdgcn_exp2f(-1.4426950408889634f * x)); }
; __device__ __forceinline__ u32x4 pack8(const f32x4 v0, const f32x4 v1) { u32x4 w; w.x = cvt_pk_bf16(v0[0], v0[1]); w.y = cvt_pk_bf16(v0[2], v0[3]); w.z = cvt_pk_bf16(v1[0], v1[1]); w.w = cvt_pk_bf16(v1[2], v1[3]); return w; }
;     __device__ __forceinline__ void a_ready(const Unit& u) const {
;         const float* p = rsv + u.pm * BM + wr_ * 64 + lane_;
;         if (n_ready & 1) { b0 = p[0]; b1 = p[HALF]; } else { a0 = p[0]; a1 = p[HALF]; }
;         ++n_ready;
;     }
;     __device__ __forceinline__ void operator()(const f32x4 (&acc)[2][2][4][2], const Unit& u, int wr, int wc, int fr, int fq) const {
;         const int row0 = u.pm * BM + wr * 64 + fr; bf16_t* base = O + u.pn * 128 + wc * 32 + 8 * fq;
;         const bool par = (n_done & 1) != 0; ++n_done;
;         const float r0 = par ? S->b0 : S->a0, r1 = par ? S->b1 : S->a1;
; #pragma unroll
;         for (int ai = 0; ai < 2; ++ai)
; #pragma unroll
;             for (int m = 0; m < 4; ++m) { const int row = row0 + ai * HALF + m * 16; bf16_t* rowp = base + (size_t)row * ldc;
;                 const float rs = __builtin_bit_cast(float, __builtin_amdgcn_ds_bpermute((m * 16 + fr) << 2, __builtin_bit_cast(int, ai ? r1 : r0)));
;                 f32x4 v[2];
; #pragma unroll
;                 for (int n = 0; n < 2; ++n) { const f32x4 a = acc[ai][0][m][n] * rs, b = acc[ai][1][m][n] * rs;
;                     v[n] = (f32x4){a[0] * sigmoid_fast(a[0]) * b[0], a[1] * sigmoid_fast(a[1]) * b[1], a[2] * sigmoid_fast(a[2]) * b[2], a[3] * sigmoid_fast(a[3]) * b[3]}; }
;                 __builtin_nontemporal_store(pack8(v[0], v[1]), (u32x4*)rowp); }
.LBB0_697:
	s_lshl_b32 s24, s57, 7
	s_ashr_i32 s25, s24, 31
	s_bitcmp0_b32 s56, 0
	s_cselect_b64 vcc, -1, 0
	s_waitcnt vmcnt(0)
	v_cndmask_b32_e32 v165, v161, v1, vcc
	v_cndmask_b32_e32 v163, v160, v152, vcc
	ds_bpermute_b32 v164, v154, v165
	v_lshl_add_u32 v162, s22, 8, v153
	s_and_b64 vcc, exec, s[2:3]
	s_cbranch_vccz .Lp6_noar
	s_bitcmp1_b32 s56, 0
	s_cbranch_scc1 .Lp6_ar_a
	global_load_dword v161, v[150:151], off
	global_load_dword v160, v[150:151], off offset:512
	s_branch .Lp6_noar
.Lp6_ar_a:
	global_load_dword v1, v[150:151], off
	global_load_dword v152, v[150:151], off offset:512
.Lp6_noar:
	v_lshl_add_u64 v[150:151], s[24:25], 1, v[142:143]
	s_andn2_b64 vcc, exec, s[2:3]
	s_waitcnt lgkmcnt(0)
	v_pk_mul_f32 v[126:127], v[126:127], v[164:165] op_sel_hi:[1,0]
	v_pk_mul_f32 v[128:129], v[128:129], v[164:165] op_sel_hi:[1,0]
	v_mul_f32_e32 v166, 0xbfb8aa3b, v126
	v_exp_f32_e32 v166, v166
	v_mul_f32_e32 v167, 0xbfb8aa3b, v127
	v_exp_f32_e32 v167, v167
	v_pk_mul_f32 v[122:123], v[122:123], v[164:165] op_sel_hi:[1,0]
	v_add_f32_e32 v166, 1.0, v166
	v_rcp_f32_e32 v166, v166
	v_add_f32_e32 v167, 1.0, v167
	v_pk_mul_f32 v[118:119], v[118:119], v[164:165] op_sel_hi:[1,0]
	v_pk_mul_f32 v[124:125], v[124:125], v[164:165] op_sel_hi:[1,0]
	v_mul_f32_e32 v126, v126, v166
	v_mul_f32_e32 v166, 0xbfb8aa3b, v128
	v_mul_f32_e32 v122, v122, v126
	v_rcp_f32_e32 v126, v167
	v_exp_f32_e32 v166, v166
	v_mul_f32_e32 v167, 0xbfb8aa3b, v129
	v_exp_f32_e32 v167, v167
	v_mul_f32_e32 v126, v127, v126
	v_add_f32_e32 v127, 1.0, v166
	v_rcp_f32_e32 v127, v127
	v_add_f32_e32 v166, 1.0, v167
	v_rcp_f32_e32 v166, v166
	v_mul_f32_e32 v123, v123, v126
	v_mul_f32_e32 v126, v128, v127
	v_mul_f32_e32 v127, 0xbfb8aa3b, v118
	v_exp_f32_e32 v127, v127
	v_mul_f32_e32 v124, v124, v126
	v_mul_f32_e32 v126, v129, v166
	v_mul_f32_e32 v125, v125, v126
	v_add_f32_e32 v126, 1.0, v127
	v_rcp_f32_e32 v126, v126
	v_pk_mul_f32 v[120:121], v[120:121], v[164:165] op_sel_hi:[1,0]
	v_mul_f32_e32 v127, 0xbfb8aa3b, v119
	v_pk_mul_f32 v[114:115], v[114:115], v[164:165] op_sel_hi:[1,0]
	v_mul_f32_e32 v118, v118, v126
	v_exp_f32_e32 v127, v127
	v_mul_f32_e32 v126, v114, v118
	v_mul_f32_e32 v118, 0xbfb8aa3b, v120
	v_exp_f32_e32 v118, v118
	v_add_f32_e32 v114, 1.0, v127
	v_mul_f32_e32 v127, 0xbfb8aa3b, v121
	v_rcp_f32_e32 v114, v114
	v_exp_f32_e32 v127, v127
	v_add_f32_e32 v118, 1.0, v118
	v_rcp_f32_e32 v118, v118
	v_mul_f32_e32 v114, v119, v114
	v_add_f32_e32 v119, 1.0, v127
	v_rcp_f32_e32 v119, v119
	v_mul_f32_e32 v127, v115, v114
	v_mul_f32_e32 v114, v120, v118
	ds_bpermute_b32 v120, v156, v165
	v_pk_mul_f32 v[116:117], v[116:117], v[164:165] op_sel_hi:[1,0]
	s_mov_b64 s[2:3], -1
	v_mul_f32_e32 v128, v116, v114
	v_mul_f32_e32 v114, v121, v119
	v_mul_f32_e32 v117, v117, v114
	v_mad_i64_i32 v[118:119], s[24:25], v162, s54, v[150:151]
	v_cvt_pk_bf16_f32 v114, v122, v123
	s_waitcnt lgkmcnt(0)
	v_pk_mul_f32 v[110:111], v[110:111], v[120:121] op_sel_hi:[1,0]
	v_cvt_pk_bf16_f32 v115, v124, v125
	v_cvt_pk_bf16_f32 v116, v126, v127
	v_cvt_pk_bf16_f32 v117, v128, v117
	flat_store_dwordx4 v[118:119], v[114:117] nt
	v_pk_mul_f32 v[112:113], v[112:113], v[120:121] op_sel_hi:[1,0]
	v_pk_mul_f32 v[106:107], v[106:107], v[120:121] op_sel_hi:[1,0]
	v_mul_f32_e32 v114, 0xbfb8aa3b, v110
	v_exp_f32_e32 v114, v114
	v_mul_f32_e32 v116, 0xbfb8aa3b, v111
	v_exp_f32_e32 v116, v116
	v_pk_mul_f32 v[102:103], v[102:103], v[120:121] op_sel_hi:[1,0]
	v_add_f32_e32 v114, 1.0, v114
	v_rcp_f32_e32 v114, v114
	v_pk_mul_f32 v[108:109], v[108:109], v[120:121] op_sel_hi:[1,0]
	v_pk_mul_f32 v[104:105], v[104:105], v[120:121] op_sel_hi:[1,0]
	v_pk_mul_f32 v[98:99], v[98:99], v[120:121] op_sel_hi:[1,0]
	v_mul_f32_e32 v110, v110, v114
	v_mul_f32_e32 v106, v106, v110
	v_add_f32_e32 v110, 1.0, v116
	v_mul_f32_e32 v114, 0xbfb8aa3b, v112
	v_rcp_f32_e32 v110, v110
	v_exp_f32_e32 v114, v114
	v_mul_f32_e32 v116, 0xbfb8aa3b, v113
	v_exp_f32_e32 v116, v116
	v_mul_f32_e32 v110, v111, v110
	v_add_f32_e32 v111, 1.0, v114
	v_rcp_f32_e32 v111, v111
	v_add_f32_e32 v114, 1.0, v116
	v_rcp_f32_e32 v114, v114
	v_mul_f32_e32 v107, v107, v110
	v_mul_f32_e32 v110, v112, v111
	v_mul_f32_e32 v111, 0xbfb8aa3b, v102
	v_exp_f32_e32 v111, v111
	v_mul_f32_e32 v108, v108, v110
	v_mul_f32_e32 v110, v113, v114
	v_mul_f32_e32 v109, v109, v110
	v_add_f32_e32 v110, 1.0, v111
	v_rcp_f32_e32 v110, v110
	v_mul_f32_e32 v111, 0xbfb8aa3b, v103
	v_exp_f32_e32 v111, v111
	v_pk_mul_f32 v[100:101], v[100:101], v[120:121] op_sel_hi:[1,0]
	v_mul_f32_e32 v102, v102, v110
	v_mul_f32_e32 v110, v98, v102
	v_mul_f32_e32 v102, 0xbfb8aa3b, v104
	v_exp_f32_e32 v102, v102
	v_add_f32_e32 v98, 1.0, v111
	v_mul_f32_e32 v111, 0xbfb8aa3b, v105
	v_rcp_f32_e32 v98, v98
	v_exp_f32_e32 v111, v111
	v_add_f32_e32 v102, 1.0, v102
	v_rcp_f32_e32 v102, v102
	v_mul_f32_e32 v98, v103, v98
	v_add_f32_e32 v103, 1.0, v111
	v_rcp_f32_e32 v103, v103
	v_mul_f32_e32 v111, v99, v98
	v_mul_f32_e32 v98, v104, v102
	ds_bpermute_b32 v104, v157, v165
	v_or_b32_e32 v115, 16, v162
	v_mul_f32_e32 v112, v100, v98
	v_mul_f32_e32 v98, v105, v103
	v_mul_f32_e32 v101, v101, v98
	v_mad_i64_i32 v[102:103], s[24:25], v115, s54, v[150:151]
	v_cvt_pk_bf16_f32 v98, v106, v107
	s_waitcnt lgkmcnt(0)
; __device__ __forceinline__ float sigmoid_fast(float x) { return __builtin_amdgcn_rcpf(1.0f + __builtin_amdgcn_exp2f(-1.4426950408889634f * x)); }
; __device__ __forceinline__ u32x4 pack8(const f32x4 v0, const f32x4 v1) { u32x4 w; w.x = cvt_pk_bf16(v0[0], v0[1]); w.y = cvt_pk_bf16(v0[2], v0[3]); w.z = cvt_pk_bf16(v1[0], v1[1]); w.w = cvt_pk_bf16(v1[2], v1[3]); return w; }
;     __device__ __forceinline__ void operator()(const f32x4 (&acc)[2][2][4][2], const Unit& u, int wr, int wc, int fr, int fq) const {
;     ...
;             for (int m = 0; m < 4; ++m) { const int row = row0 + ai * HALF + m * 16; bf16_t* rowp = base + (size_t)row * ldc;
;                 const float rs = __builtin_bit_cast(float, __builtin_amdgcn_ds_bpermute((m * 16 + fr) << 2, __builtin_bit_cast(int, ai ? r1 : r0)));
;                 f32x4 v[2];
; #pragma unroll
;                 for (int n = 0; n < 2; ++n) { const f32x4 a = acc[ai][0][m][n] * rs, b = acc[ai][1][m][n] * rs;
;                     v[n] = (f32x4){a[0] * sigmoid_fast(a[0]) * b[0], a[1] * sigmoid_fast(a[1]) * b[1], a[2] * sigmoid_fast(a[2]) * b[2], a[3] * sigmoid_fast(a[3]) * b[3]}; }
;                 __builtin_nontemporal_store(pack8(v[0], v[1]), (u32x4*)rowp); }
	v_pk_mul_f32 v[94:95], v[94:95], v[104:105] op_sel_hi:[1,0]
	v_cvt_pk_bf16_f32 v99, v108, v109
	v_cvt_pk_bf16_f32 v100, v110, v111
	v_cvt_pk_bf16_f32 v101, v112, v101
	flat_store_dwordx4 v[102:103], v[98:101] nt
	v_pk_mul_f32 v[96:97], v[96:97], v[104:105] op_sel_hi:[1,0]
	v_pk_mul_f32 v[90:91], v[90:91], v[104:105] op_sel_hi:[1,0]
	v_mul_f32_e32 v98, 0xbfb8aa3b, v94
	v_exp_f32_e32 v98, v98
	v_mul_f32_e32 v100, 0xbfb8aa3b, v95
	v_exp_f32_e32 v100, v100
	v_pk_mul_f32 v[86:87], v[86:87], v[104:105] op_sel_hi:[1,0]
	v_add_f32_e32 v98, 1.0, v98
	v_rcp_f32_e32 v98, v98
	v_pk_mul_f32 v[92:93], v[92:93], v[104:105] op_sel_hi:[1,0]
	v_pk_mul_f32 v[88:89], v[88:89], v[104:105] op_sel_hi:[1,0]
	v_pk_mul_f32 v[82:83], v[82:83], v[104:105] op_sel_hi:[1,0]
	v_mul_f32_e32 v94, v94, v98
	v_mul_f32_e32 v90, v90, v94
	v_add_f32_e32 v94, 1.0, v100
	v_mul_f32_e32 v98, 0xbfb8aa3b, v96
	v_rcp_f32_e32 v94, v94
	v_exp_f32_e32 v98, v98
	v_mul_f32_e32 v100, 0xbfb8aa3b, v97
	v_exp_f32_e32 v100, v100
	v_mul_f32_e32 v94, v95, v94
	v_add_f32_e32 v95, 1.0, v98
	v_rcp_f32_e32 v95, v95
	v_add_f32_e32 v98, 1.0, v100
	v_rcp_f32_e32 v98, v98
	v_mul_f32_e32 v91, v91, v94
	v_mul_f32_e32 v94, v96, v95
	v_mul_f32_e32 v95, 0xbfb8aa3b, v86
	v_exp_f32_e32 v95, v95
	v_mul_f32_e32 v92, v92, v94
	v_mul_f32_e32 v94, v97, v98
	v_mul_f32_e32 v93, v93, v94
	v_add_f32_e32 v94, 1.0, v95
	v_rcp_f32_e32 v94, v94
	v_mul_f32_e32 v95, 0xbfb8aa3b, v87
	v_exp_f32_e32 v95, v95
	v_pk_mul_f32 v[84:85], v[84:85], v[104:105] op_sel_hi:[1,0]
	v_mul_f32_e32 v86, v86, v94
	v_mul_f32_e32 v94, v82, v86
	v_mul_f32_e32 v86, 0xbfb8aa3b, v88
	v_exp_f32_e32 v86, v86
	v_add_f32_e32 v82, 1.0, v95
	v_mul_f32_e32 v95, 0xbfb8aa3b, v89
	v_rcp_f32_e32 v82, v82
	v_exp_f32_e32 v95, v95
	v_add_f32_e32 v86, 1.0, v86
	v_rcp_f32_e32 v86, v86
	v_mul_f32_e32 v82, v87, v82
	v_add_f32_e32 v87, 1.0, v95
	v_rcp_f32_e32 v87, v87
	v_mul_f32_e32 v95, v83, v82
	v_mul_f32_e32 v82, v88, v86
	ds_bpermute_b32 v88, v158, v165
	v_or_b32_e32 v99, 32, v162
	v_mul_f32_e32 v96, v84, v82
	v_mul_f32_e32 v82, v89, v87
	v_mul_f32_e32 v85, v85, v82
	v_mad_i64_i32 v[86:87], s[24:25], v99, s54, v[150:151]
	v_cvt_pk_bf16_f32 v82, v90, v91
	s_waitcnt lgkmcnt(0)
	v_pk_mul_f32 v[78:79], v[78:79], v[88:89] op_sel_hi:[1,0]
	v_cvt_pk_bf16_f32 v83, v92, v93
	v_cvt_pk_bf16_f32 v84, v94, v95
	v_cvt_pk_bf16_f32 v85, v96, v85
	flat_store_dwordx4 v[86:87], v[82:85] nt
	v_pk_mul_f32 v[80:81], v[80:81], v[88:89] op_sel_hi:[1,0]
	v_pk_mul_f32 v[74:75], v[74:75], v[88:89] op_sel_hi:[1,0]
	v_mul_f32_e32 v82, 0xbfb8aa3b, v78
	v_exp_f32_e32 v82, v82
	v_mul_f32_e32 v84, 0xbfb8aa3b, v79
	v_exp_f32_e32 v84, v84
	v_pk_mul_f32 v[70:71], v[70:71], v[88:89] op_sel_hi:[1,0]
	v_add_f32_e32 v82, 1.0, v82
	v_rcp_f32_e32 v82, v82
	v_pk_mul_f32 v[76:77], v[76:77], v[88:89] op_sel_hi:[1,0]
	v_pk_mul_f32 v[72:73], v[72:73], v[88:89] op_sel_hi:[1,0]
	v_pk_mul_f32 v[66:67], v[66:67], v[88:89] op_sel_hi:[1,0]
	v_mul_f32_e32 v78, v78, v82
	v_mul_f32_e32 v74, v74, v78
	v_add_f32_e32 v78, 1.0, v84
	v_mul_f32_e32 v82, 0xbfb8aa3b, v80
	v_rcp_f32_e32 v78, v78
	v_exp_f32_e32 v82, v82
	v_mul_f32_e32 v84, 0xbfb8aa3b, v81
	v_exp_f32_e32 v84, v84
	v_mul_f32_e32 v78, v79, v78
	v_add_f32_e32 v79, 1.0, v82
	v_rcp_f32_e32 v79, v79
	v_add_f32_e32 v82, 1.0, v84
	v_rcp_f32_e32 v82, v82
	v_mul_f32_e32 v75, v75, v78
	v_mul_f32_e32 v78, v80, v79
	v_mul_f32_e32 v79, 0xbfb8aa3b, v70
	v_exp_f32_e32 v79, v79
	v_mul_f32_e32 v76, v76, v78
	v_mul_f32_e32 v78, v81, v82
	v_mul_f32_e32 v77, v77, v78
	v_add_f32_e32 v78, 1.0, v79
	v_rcp_f32_e32 v78, v78
	v_mul_f32_e32 v79, 0xbfb8aa3b, v71
	v_exp_f32_e32 v79, v79
	v_pk_mul_f32 v[68:69], v[68:69], v[88:89] op_sel_hi:[1,0]
	v_mul_f32_e32 v70, v70, v78
	v_mul_f32_e32 v78, v66, v70
	v_mul_f32_e32 v70, 0xbfb8aa3b, v72
	v_exp_f32_e32 v70, v70
	v_add_f32_e32 v66, 1.0, v79
	v_mul_f32_e32 v79, 0xbfb8aa3b, v73
	v_rcp_f32_e32 v66, v66
	v_exp_f32_e32 v79, v79
	v_add_f32_e32 v70, 1.0, v70
	v_rcp_f32_e32 v70, v70
	v_mul_f32_e32 v66, v71, v66
	v_add_f32_e32 v71, 1.0, v79
	v_rcp_f32_e32 v71, v71
	v_mul_f32_e32 v79, v67, v66
	v_mul_f32_e32 v66, v72, v70
	ds_bpermute_b32 v72, v154, v163
	v_or_b32_e32 v83, 48, v162
	v_mul_f32_e32 v80, v68, v66
	v_mul_f32_e32 v66, v73, v71
	v_mul_f32_e32 v69, v69, v66
	v_mad_i64_i32 v[70:71], s[24:25], v83, s54, v[150:151]
	v_cvt_pk_bf16_f32 v66, v74, v75
	s_waitcnt lgkmcnt(0)
	v_pk_mul_f32 v[62:63], v[62:63], v[72:73] op_sel_hi:[1,0]
	v_cvt_pk_bf16_f32 v67, v76, v77
	v_cvt_pk_bf16_f32 v68, v78, v79
	v_cvt_pk_bf16_f32 v69, v80, v69
	flat_store_dwordx4 v[70:71], v[66:69] nt
	v_pk_mul_f32 v[64:65], v[64:65], v[72:73] op_sel_hi:[1,0]
	v_pk_mul_f32 v[58:59], v[58:59], v[72:73] op_sel_hi:[1,0]
	v_mul_f32_e32 v66, 0xbfb8aa3b, v62
	v_exp_f32_e32 v66, v66
	v_mul_f32_e32 v68, 0xbfb8aa3b, v63
	v_exp_f32_e32 v68, v68
	v_pk_mul_f32 v[54:55], v[54:55], v[72:73] op_sel_hi:[1,0]
	v_add_f32_e32 v66, 1.0, v66
	v_rcp_f32_e32 v66, v66
	v_pk_mul_f32 v[60:61], v[60:61], v[72:73] op_sel_hi:[1,0]
	v_pk_mul_f32 v[56:57], v[56:57], v[72:73] op_sel_hi:[1,0]
	v_pk_mul_f32 v[50:51], v[50:51], v[72:73] op_sel_hi:[1,0]
	v_mul_f32_e32 v62, v62, v66
	v_mul_f32_e32 v58, v58, v62
	v_add_f32_e32 v62, 1.0, v68
	v_mul_f32_e32 v66, 0xbfb8aa3b, v64
	v_rcp_f32_e32 v62, v62
	v_exp_f32_e32 v66, v66
	v_mul_f32_e32 v68, 0xbfb8aa3b, v65
	v_exp_f32_e32 v68, v68
	v_mul_f32_e32 v62, v63, v62
	v_add_f32_e32 v63, 1.0, v66
	v_rcp_f32_e32 v63, v63
	v_add_f32_e32 v66, 1.0, v68
	v_rcp_f32_e32 v66, v66
	v_mul_f32_e32 v59, v59, v62
	v_mul_f32_e32 v62, v64, v63
	v_mul_f32_e32 v63, 0xbfb8aa3b, v54
	v_exp_f32_e32 v63, v63
	v_mul_f32_e32 v60, v60, v62
	v_mul_f32_e32 v62, v65, v66
	v_mul_f32_e32 v61, v61, v62
	v_add_f32_e32 v62, 1.0, v63
	v_rcp_f32_e32 v62, v62
	v_mul_f32_e32 v63, 0xbfb8aa3b, v55
	v_exp_f32_e32 v63, v63
	v_pk_mul_f32 v[52:53], v[52:53], v[72:73] op_sel_hi:[1,0]
	v_mul_f32_e32 v54, v54, v62
	v_mul_f32_e32 v62, v50, v54
	v_mul_f32_e32 v54, 0xbfb8aa3b, v56
	v_exp_f32_e32 v54, v54
	v_add_f32_e32 v50, 1.0, v63
	v_mul_f32_e32 v63, 0xbfb8aa3b, v57
	v_rcp_f32_e32 v50, v50
	v_exp_f32_e32 v63, v63
	v_add_f32_e32 v54, 1.0, v54
	v_rcp_f32_e32 v54, v54
	v_mul_f32_e32 v50, v55, v50
	v_add_f32_e32 v55, 1.0, v63
	v_rcp_f32_e32 v55, v55
	v_mul_f32_e32 v63, v51, v50
	v_mul_f32_e32 v50, v56, v54
	ds_bpermute_b32 v56, v156, v163
	v_add_u32_e32 v67, 0x80, v162
	v_mul_f32_e32 v64, v52, v50
	v_mul_f32_e32 v50, v57, v55
	v_mul_f32_e32 v53, v53, v50
	v_mad_i64_i32 v[54:55], s[24:25], v67, s54, v[150:151]
	v_cvt_pk_bf16_f32 v50, v58, v59
	s_waitcnt lgkmcnt(0)
; __device__ __forceinline__ float sigmoid_fast(float x) { return __builtin_amdgcn_rcpf(1.0f + __builtin_amdgcn_exp2f(-1.4426950408889634f * x)); }
; __device__ __forceinline__ u32x4 pack8(const f32x4 v0, const f32x4 v1) { u32x4 w; w.x = cvt_pk_bf16(v0[0], v0[1]); w.y = cvt_pk_bf16(v0[2], v0[3]); w.z = cvt_pk_bf16(v1[0], v1[1]); w.w = cvt_pk_bf16(v1[2], v1[3]); return w; }
; #define PG8_BAR __builtin_amdgcn_s_barrier()
;     __device__ __forceinline__ void operator()(const f32x4 (&acc)[2][2][4][2], const Unit& u, int wr, int wc, int fr, int fq) const {
;     ...
;             for (int m = 0; m < 4; ++m) { const int row = row0 + ai * HALF + m * 16; bf16_t* rowp = base + (size_t)row * ldc;
;                 const float rs = __builtin_bit_cast(float, __builtin_amdgcn_ds_bpermute((m * 16 + fr) << 2, __builtin_bit_cast(int, ai ? r1 : r0)));
;                 f32x4 v[2];
; #pragma unroll
;                 for (int n = 0; n < 2; ++n) { const f32x4 a = acc[ai][0][m][n] * rs, b = acc[ai][1][m][n] * rs;
;                     v[n] = (f32x4){a[0] * sigmoid_fast(a[0]) * b[0], a[1] * sigmoid_fast(a[1]) * b[1], a[2] * sigmoid_fast(a[2]) * b[2], a[3] * sigmoid_fast(a[3]) * b[3]}; }
;                 __builtin_nontemporal_store(pack8(v[0], v[1]), (u32x4*)rowp); }
; template <class Epi, class Sched, bool ALIGN_EPI = false, bool SP2 = false>
; __device__ __forceinline__ void gemm_phase(PG8_LAS unsigned char* lds, const Gemm g, const Sched& S, const Epi& E) {
;     ...
;         if constexpr (ALIGN_EPI) { if (wr == 0) PG8_BAR; }
;         if constexpr (!Epi::AFTER_DRAIN) { E(acc, cur, wr, wc, fr, fq); S.done(cur); }
;         if (!has_next) break;
; #pragma unroll
;         for (int a = 0; a < 2; ++a)
; #pragma unroll
;             for (int b = 0; b < 2; ++b)
; #pragma unroll
;                 for (int m = 0; m < 4; ++m)
; #pragma unroll
;                     for (int n = 0; n < 2; ++n) acc[a][b][m][n] = (f32x4){0.f, 0.f, 0.f, 0.f};
;         cur = nxt; cA = nA; cB = nB; ++ui;
;         if constexpr (ALIGN_EPI) { if (wr == 1) PG8_BAR; }
	v_pk_mul_f32 v[46:47], v[46:47], v[56:57] op_sel_hi:[1,0]
	v_cvt_pk_bf16_f32 v51, v60, v61
	v_cvt_pk_bf16_f32 v52, v62, v63
	v_cvt_pk_bf16_f32 v53, v64, v53
	flat_store_dwordx4 v[54:55], v[50:53] nt
	v_pk_mul_f32 v[48:49], v[48:49], v[56:57] op_sel_hi:[1,0]
	v_pk_mul_f32 v[42:43], v[42:43], v[56:57] op_sel_hi:[1,0]
	v_mul_f32_e32 v50, 0xbfb8aa3b, v46
	v_exp_f32_e32 v50, v50
	v_mul_f32_e32 v52, 0xbfb8aa3b, v47
	v_exp_f32_e32 v52, v52
	v_pk_mul_f32 v[38:39], v[38:39], v[56:57] op_sel_hi:[1,0]
	v_add_f32_e32 v50, 1.0, v50
	v_rcp_f32_e32 v50, v50
	v_pk_mul_f32 v[44:45], v[44:45], v[56:57] op_sel_hi:[1,0]
	v_pk_mul_f32 v[40:41], v[40:41], v[56:57] op_sel_hi:[1,0]
	v_pk_mul_f32 v[34:35], v[34:35], v[56:57] op_sel_hi:[1,0]
	v_mul_f32_e32 v46, v46, v50
	v_mul_f32_e32 v42, v42, v46
	v_add_f32_e32 v46, 1.0, v52
	v_mul_f32_e32 v50, 0xbfb8aa3b, v48
	v_rcp_f32_e32 v46, v46
	v_exp_f32_e32 v50, v50
	v_mul_f32_e32 v52, 0xbfb8aa3b, v49
	v_exp_f32_e32 v52, v52
	v_mul_f32_e32 v46, v47, v46
	v_add_f32_e32 v47, 1.0, v50
	v_rcp_f32_e32 v47, v47
	v_add_f32_e32 v50, 1.0, v52
	v_rcp_f32_e32 v50, v50
	v_mul_f32_e32 v43, v43, v46
	v_mul_f32_e32 v46, v48, v47
	v_mul_f32_e32 v47, 0xbfb8aa3b, v38
	v_exp_f32_e32 v47, v47
	v_mul_f32_e32 v44, v44, v46
	v_mul_f32_e32 v46, v49, v50
	v_mul_f32_e32 v45, v45, v46
	v_add_f32_e32 v46, 1.0, v47
	v_rcp_f32_e32 v46, v46
	v_mul_f32_e32 v47, 0xbfb8aa3b, v39
	v_exp_f32_e32 v47, v47
	v_pk_mul_f32 v[36:37], v[36:37], v[56:57] op_sel_hi:[1,0]
	v_mul_f32_e32 v38, v38, v46
	v_mul_f32_e32 v46, v34, v38
	v_mul_f32_e32 v38, 0xbfb8aa3b, v40
	v_exp_f32_e32 v38, v38
	v_add_f32_e32 v34, 1.0, v47
	v_mul_f32_e32 v47, 0xbfb8aa3b, v41
	v_rcp_f32_e32 v34, v34
	v_exp_f32_e32 v47, v47
	v_add_f32_e32 v38, 1.0, v38
	v_rcp_f32_e32 v38, v38
	v_mul_f32_e32 v34, v39, v34
	v_add_f32_e32 v39, 1.0, v47
	v_rcp_f32_e32 v39, v39
	v_mul_f32_e32 v47, v35, v34
	v_mul_f32_e32 v34, v40, v38
	ds_bpermute_b32 v40, v157, v163
	v_add_u32_e32 v51, 0x90, v162
	v_mul_f32_e32 v48, v36, v34
	v_mul_f32_e32 v34, v41, v39
	v_mul_f32_e32 v37, v37, v34
	v_mad_i64_i32 v[38:39], s[24:25], v51, s54, v[150:151]
	v_cvt_pk_bf16_f32 v34, v42, v43
	s_waitcnt lgkmcnt(0)
	v_pk_mul_f32 v[30:31], v[30:31], v[40:41] op_sel_hi:[1,0]
	v_cvt_pk_bf16_f32 v35, v44, v45
	v_cvt_pk_bf16_f32 v36, v46, v47
	v_cvt_pk_bf16_f32 v37, v48, v37
	flat_store_dwordx4 v[38:39], v[34:37] nt
	v_pk_mul_f32 v[32:33], v[32:33], v[40:41] op_sel_hi:[1,0]
	v_pk_mul_f32 v[26:27], v[26:27], v[40:41] op_sel_hi:[1,0]
	v_mul_f32_e32 v34, 0xbfb8aa3b, v30
	v_exp_f32_e32 v34, v34
	v_mul_f32_e32 v36, 0xbfb8aa3b, v31
	v_exp_f32_e32 v36, v36
	v_pk_mul_f32 v[22:23], v[22:23], v[40:41] op_sel_hi:[1,0]
	v_add_f32_e32 v34, 1.0, v34
	v_rcp_f32_e32 v34, v34
	v_pk_mul_f32 v[28:29], v[28:29], v[40:41] op_sel_hi:[1,0]
	v_pk_mul_f32 v[24:25], v[24:25], v[40:41] op_sel_hi:[1,0]
	v_pk_mul_f32 v[18:19], v[18:19], v[40:41] op_sel_hi:[1,0]
	v_mul_f32_e32 v30, v30, v34
	v_mul_f32_e32 v26, v26, v30
	v_add_f32_e32 v30, 1.0, v36
	v_mul_f32_e32 v34, 0xbfb8aa3b, v32
	v_rcp_f32_e32 v30, v30
	v_exp_f32_e32 v34, v34
	v_mul_f32_e32 v36, 0xbfb8aa3b, v33
	v_exp_f32_e32 v36, v36
	v_mul_f32_e32 v30, v31, v30
	v_add_f32_e32 v31, 1.0, v34
	v_rcp_f32_e32 v31, v31
	v_add_f32_e32 v34, 1.0, v36
	v_rcp_f32_e32 v34, v34
	v_mul_f32_e32 v27, v27, v30
	v_mul_f32_e32 v30, v32, v31
	v_mul_f32_e32 v31, 0xbfb8aa3b, v22
	v_exp_f32_e32 v31, v31
	v_mul_f32_e32 v28, v28, v30
	v_mul_f32_e32 v30, v33, v34
	v_mul_f32_e32 v29, v29, v30
	v_add_f32_e32 v30, 1.0, v31
	v_rcp_f32_e32 v30, v30
	v_mul_f32_e32 v31, 0xbfb8aa3b, v23
	v_exp_f32_e32 v31, v31
	v_pk_mul_f32 v[20:21], v[20:21], v[40:41] op_sel_hi:[1,0]
	v_mul_f32_e32 v22, v22, v30
	v_mul_f32_e32 v30, v18, v22
	v_mul_f32_e32 v22, 0xbfb8aa3b, v24
	v_exp_f32_e32 v22, v22
	v_add_f32_e32 v18, 1.0, v31
	v_mul_f32_e32 v31, 0xbfb8aa3b, v25
	v_rcp_f32_e32 v18, v18
	v_exp_f32_e32 v31, v31
	v_add_f32_e32 v22, 1.0, v22
	v_rcp_f32_e32 v22, v22
	v_mul_f32_e32 v18, v23, v18
	v_add_f32_e32 v23, 1.0, v31
	v_rcp_f32_e32 v23, v23
	v_mul_f32_e32 v31, v19, v18
	v_mul_f32_e32 v18, v24, v22
	ds_bpermute_b32 v24, v158, v163
	v_add_u32_e32 v35, 0xa0, v162
	v_mul_f32_e32 v32, v20, v18
	v_mul_f32_e32 v18, v25, v23
	v_mul_f32_e32 v21, v21, v18
	v_mad_i64_i32 v[22:23], s[24:25], v35, s54, v[150:151]
	v_cvt_pk_bf16_f32 v18, v26, v27
	s_waitcnt lgkmcnt(0)
	v_pk_mul_f32 v[14:15], v[14:15], v[24:25] op_sel_hi:[1,0]
	v_cvt_pk_bf16_f32 v19, v28, v29
	v_cvt_pk_bf16_f32 v20, v30, v31
	v_cvt_pk_bf16_f32 v21, v32, v21
	flat_store_dwordx4 v[22:23], v[18:21] nt
	v_pk_mul_f32 v[16:17], v[16:17], v[24:25] op_sel_hi:[1,0]
	v_pk_mul_f32 v[10:11], v[10:11], v[24:25] op_sel_hi:[1,0]
	v_mul_f32_e32 v18, 0xbfb8aa3b, v14
	v_exp_f32_e32 v18, v18
	v_mul_f32_e32 v20, 0xbfb8aa3b, v15
	v_exp_f32_e32 v20, v20
	v_pk_mul_f32 v[6:7], v[6:7], v[24:25] op_sel_hi:[1,0]
	v_add_f32_e32 v18, 1.0, v18
	v_rcp_f32_e32 v18, v18
	v_pk_mul_f32 v[12:13], v[12:13], v[24:25] op_sel_hi:[1,0]
	v_pk_mul_f32 v[8:9], v[8:9], v[24:25] op_sel_hi:[1,0]
	v_pk_mul_f32 v[2:3], v[2:3], v[24:25] op_sel_hi:[1,0]
	v_mul_f32_e32 v14, v14, v18
	v_mul_f32_e32 v10, v10, v14
	v_add_f32_e32 v14, 1.0, v20
	v_mul_f32_e32 v18, 0xbfb8aa3b, v16
	v_rcp_f32_e32 v14, v14
	v_exp_f32_e32 v18, v18
	v_mul_f32_e32 v20, 0xbfb8aa3b, v17
	v_exp_f32_e32 v20, v20
	v_mul_f32_e32 v14, v15, v14
	v_add_f32_e32 v15, 1.0, v18
	v_rcp_f32_e32 v15, v15
	v_add_f32_e32 v18, 1.0, v20
	v_rcp_f32_e32 v18, v18
	v_mul_f32_e32 v11, v11, v14
	v_mul_f32_e32 v14, v16, v15
	v_mul_f32_e32 v15, 0xbfb8aa3b, v6
	v_exp_f32_e32 v15, v15
	v_mul_f32_e32 v12, v12, v14
	v_mul_f32_e32 v14, v17, v18
	v_mul_f32_e32 v13, v13, v14
	v_add_f32_e32 v14, 1.0, v15
	v_rcp_f32_e32 v14, v14
	v_mul_f32_e32 v15, 0xbfb8aa3b, v7
	v_exp_f32_e32 v15, v15
	v_pk_mul_f32 v[4:5], v[4:5], v[24:25] op_sel_hi:[1,0]
	v_mul_f32_e32 v6, v6, v14
	v_mul_f32_e32 v14, v2, v6
	v_mul_f32_e32 v6, 0xbfb8aa3b, v8
	v_add_f32_e32 v2, 1.0, v15
	v_exp_f32_e32 v6, v6
	v_mul_f32_e32 v15, 0xbfb8aa3b, v9
	v_rcp_f32_e32 v2, v2
	v_exp_f32_e32 v15, v15
	v_add_f32_e32 v6, 1.0, v6
	v_rcp_f32_e32 v6, v6
	v_mul_f32_e32 v2, v7, v2
	v_add_f32_e32 v7, 1.0, v15
	v_rcp_f32_e32 v7, v7
	v_mul_f32_e32 v15, v3, v2
	v_mul_f32_e32 v2, v8, v6
	v_add_u32_e32 v19, 0xb0, v162
	v_mul_f32_e32 v8, v4, v2
	v_mul_f32_e32 v2, v9, v7
	v_mul_f32_e32 v5, v5, v2
	v_mad_i64_i32 v[6:7], s[24:25], v19, s54, v[150:151]
	v_cvt_pk_bf16_f32 v2, v10, v11
	v_cvt_pk_bf16_f32 v3, v12, v13
	v_cvt_pk_bf16_f32 v4, v14, v15
	v_cvt_pk_bf16_f32 v5, v8, v5
	flat_store_dwordx4 v[6:7], v[2:5] nt
	s_cbranch_vccnz .LBB0_688
	s_andn2_b64 vcc, exec, s[4:5]
	s_cbranch_vccnz .LBB0_687
	s_barrier
	s_branch .LBB0_687
